# P1 tail half-unit K-loop: all 8 waves on one schedule, one barrier per K-tile, next K-tile fragments read into the unused acc[1] registers under the MFMAs; 6-K-tile loop body
# baseline (speedup 1.0000x reference)
.LBB0_104:
	s_ashr_i32 s65, s64, 31
	s_lshl_b64 s[2:3], s[64:65], 19
	s_add_u32 s2, s80, s2
	s_addc_u32 s3, s81, s3
	s_cmp_gt_i32 s42, 0
	s_cselect_b32 s4, 0x40000, 0
	s_add_u32 s68, s2, s4
	s_addc_u32 s69, s3, 0
	s_and_b64 s[2:3], s[66:67], exec
	s_cselect_b32 s4, s69, s77
	s_cselect_b32 s43, s68, s76
	s_ashr_i32 s63, s62, 31
	s_lshl_b64 s[2:3], s[62:63], 19
	s_add_u32 s70, s10, s2
	s_addc_u32 s71, s11, s3
	s_and_b64 s[2:3], s[66:67], exec
	s_cselect_b32 s63, s71, s1
	s_cselect_b32 s65, s70, s0
	s_cmp_lt_i32 s33, 0
	v_mov_b32_e32 v4, v2
	v_mov_b32_e32 v5, v2
	s_cselect_b64 s[86:87], -1, 0
	s_add_u32 s36, s0, 0x100
	v_mov_b32_e32 v3, v2
	v_mov_b32_e32 v86, 0
	v_mov_b64_e32 v[24:25], v[4:5]
	v_mov_b64_e32 v[56:57], v[4:5]
	v_mov_b64_e32 v[28:29], v[4:5]
	v_mov_b64_e32 v[60:61], v[4:5]
	v_mov_b64_e32 v[36:37], v[4:5]
	v_mov_b64_e32 v[68:69], v[4:5]
	v_mov_b64_e32 v[32:33], v[4:5]
	v_mov_b64_e32 v[64:65], v[4:5]
	v_mov_b64_e32 v[12:13], v[4:5]
	v_mov_b64_e32 v[44:45], v[4:5]
	v_mov_b64_e32 v[16:17], v[4:5]
	v_mov_b64_e32 v[48:49], v[4:5]
	v_mov_b64_e32 v[20:21], v[4:5]
	v_mov_b64_e32 v[52:53], v[4:5]
	v_mov_b64_e32 v[8:9], v[4:5]
	v_mov_b64_e32 v[40:41], v[4:5]
	s_addc_u32 s44, s1, 0
	s_mov_b32 s45, -2
	v_mov_b64_e32 v[22:23], v[2:3]
	v_mov_b64_e32 v[54:55], v[2:3]
	v_mov_b64_e32 v[26:27], v[2:3]
	v_mov_b64_e32 v[58:59], v[2:3]
	v_mov_b64_e32 v[34:35], v[2:3]
	v_mov_b64_e32 v[66:67], v[2:3]
	v_mov_b64_e32 v[30:31], v[2:3]
	v_mov_b64_e32 v[62:63], v[2:3]
	v_mov_b64_e32 v[10:11], v[2:3]
	v_mov_b64_e32 v[42:43], v[2:3]
	v_mov_b64_e32 v[14:15], v[2:3]
	v_mov_b64_e32 v[46:47], v[2:3]
	v_mov_b64_e32 v[18:19], v[2:3]
	v_mov_b64_e32 v[50:51], v[2:3]
	v_mov_b64_e32 v[6:7], v[2:3]
	v_mov_b64_e32 v[38:39], v[2:3]
	v_mov_b32_e32 v87, v86
	v_mov_b32_e32 v88, v86
	v_mov_b32_e32 v89, v86
	v_mov_b32_e32 v118, v86
	v_mov_b32_e32 v119, v86
	v_mov_b32_e32 v120, v86
	v_mov_b32_e32 v121, v86
	v_mov_b32_e32 v90, v86
	v_mov_b32_e32 v91, v86
	v_mov_b32_e32 v92, v86
	v_mov_b32_e32 v93, v86
	v_mov_b32_e32 v122, v86
	v_mov_b32_e32 v123, v86
	v_mov_b32_e32 v124, v86
	v_mov_b32_e32 v125, v86
	v_mov_b32_e32 v94, v86
	v_mov_b32_e32 v95, v86
	v_mov_b32_e32 v96, v86
	v_mov_b32_e32 v97, v86
	v_mov_b32_e32 v126, v86
	v_mov_b32_e32 v127, v86
	v_mov_b32_e32 v128, v86
	v_mov_b32_e32 v129, v86
	v_mov_b32_e32 v98, v86
	v_mov_b32_e32 v99, v86
	v_mov_b32_e32 v100, v86
	v_mov_b32_e32 v101, v86
	v_mov_b32_e32 v130, v86
	v_mov_b32_e32 v131, v86
	v_mov_b32_e32 v132, v86
	v_mov_b32_e32 v133, v86
	v_mov_b32_e32 v74, v86
	v_mov_b32_e32 v75, v86
	v_mov_b32_e32 v76, v86
	v_mov_b32_e32 v77, v86
	v_mov_b32_e32 v106, v86
	v_mov_b32_e32 v107, v86
	v_mov_b32_e32 v108, v86
	v_mov_b32_e32 v109, v86
	v_mov_b32_e32 v78, v86
	v_mov_b32_e32 v79, v86
	v_mov_b32_e32 v80, v86
	v_mov_b32_e32 v81, v86
	v_mov_b32_e32 v110, v86
	v_mov_b32_e32 v111, v86
	v_mov_b32_e32 v112, v86
	v_mov_b32_e32 v113, v86
	v_mov_b32_e32 v82, v86
	v_mov_b32_e32 v83, v86
	v_mov_b32_e32 v84, v86
	v_mov_b32_e32 v85, v86
	v_mov_b32_e32 v114, v86
	v_mov_b32_e32 v115, v86
	v_mov_b32_e32 v116, v86
	v_mov_b32_e32 v117, v86
	v_mov_b32_e32 v70, v86
	v_mov_b32_e32 v71, v86
	v_mov_b32_e32 v72, v86
	v_mov_b32_e32 v73, v86
	v_mov_b32_e32 v102, v86
	v_mov_b32_e32 v103, v86
	v_mov_b32_e32 v104, v86
	v_mov_b32_e32 v105, v86
	s_and_b64 vcc, exec, s[86:87]
	s_cbranch_vccnz .LBB0_107
	s_add_u32 s2, s0, 0x100
	s_addc_u32 s3, s1, 0
	s_add_u32 s84, s76, 0x100
	s_addc_u32 s85, s77, 0
	s_mov_b32 s45, 0
	s_waitcnt vmcnt(0)
	s_and_b64 vcc, exec, s[14:15]
	s_cbranch_vccz .Lhu_in
	s_barrier
.Lhu_in:
	ds_read_b128 v[150:153], v248
	ds_read_b128 v[154:157], v248 offset:1024
	ds_read_b128 v[158:161], v248 offset:2048
	ds_read_b128 v[162:165], v248 offset:3072
	ds_read_b128 v[134:137], v249
	ds_read_b128 v[138:141], v249 offset:1024
	ds_read_b128 v[142:145], v249 offset:2048
	ds_read_b128 v[146:149], v249 offset:3072
	ds_read_b128 v[166:169], v250
	ds_read_b128 v[170:173], v250 offset:1024
	ds_read_b128 v[174:177], v250 offset:2048
	ds_read_b128 v[178:181], v250 offset:3072
	ds_read_b128 v[182:185], v250 offset:4096
	ds_read_b128 v[186:189], v250 offset:5120
	ds_read_b128 v[190:193], v250 offset:6144
	ds_read_b128 v[194:197], v250 offset:7168
	v_lshl_add_u64 v[220:221], s[2:3], 0, v[208:209]
	v_lshl_add_u64 v[222:223], s[2:3], 0, v[212:213]
	s_add_u32 s88, s2, 0x40000
	s_addc_u32 s89, s3, 0
	v_lshl_add_u64 v[224:225], s[88:89], 0, v[208:209]
	v_lshl_add_u64 v[252:253], s[88:89], 0, v[212:213]
	s_add_u32 s2, s2, 0x80
	s_addc_u32 s3, s3, 0
	s_add_i32 m0, s61, 0xc000
	s_nop 0
	global_load_lds_dwordx4 v[220:221], off
	s_add_i32 m0, s61, 0xe000
	s_nop 0
	global_load_lds_dwordx4 v[222:223], off
	s_add_i32 m0, s61, 0x20000
	s_nop 0
	global_load_lds_dwordx4 v[224:225], off
	s_add_i32 m0, s61, 0x22000
	s_nop 0
	global_load_lds_dwordx4 v[252:253], off
	v_lshl_add_u64 v[220:221], s[84:85], 0, v[206:207]
	v_lshl_add_u64 v[222:223], s[84:85], 0, v[210:211]
	s_add_u32 s84, s84, 0x80
	s_addc_u32 s85, s85, 0
	s_mov_b32 m0, s95
	s_nop 0
	global_load_lds_dwordx4 v[220:221], off
	s_mov_b32 m0, s96
	s_nop 0
	global_load_lds_dwordx4 v[222:223], off
.Lhu_loop:
	s_waitcnt vmcnt(6)
	s_waitcnt lgkmcnt(0)
	s_barrier
	v_add_u32_e32 v3, 0x18000, v247
	v_add_u32_e32 v4, 0x1c000, v247
	ds_read_b128 v[22:25], v3
	ds_read_b128 v[26:29], v3 offset:1024
	ds_read_b128 v[30:33], v3 offset:2048
	ds_read_b128 v[34:37], v3 offset:3072
	ds_read_b128 v[6:9], v4
	ds_read_b128 v[10:13], v4 offset:1024
	ds_read_b128 v[14:17], v4 offset:2048
	ds_read_b128 v[18:21], v4 offset:3072
	ds_read_b128 v[38:41], v250 offset:32768
	ds_read_b128 v[42:45], v250 offset:33792
	ds_read_b128 v[46:49], v250 offset:34816
	ds_read_b128 v[50:53], v250 offset:35840
	ds_read_b128 v[54:57], v250 offset:36864
	ds_read_b128 v[58:61], v250 offset:37888
	ds_read_b128 v[62:65], v250 offset:38912
	ds_read_b128 v[66:69], v250 offset:39936
	v_lshl_add_u64 v[220:221], s[2:3], 0, v[208:209]
	v_lshl_add_u64 v[222:223], s[2:3], 0, v[212:213]
	s_add_u32 s88, s2, 0x40000
	s_addc_u32 s89, s3, 0
	v_lshl_add_u64 v[224:225], s[88:89], 0, v[208:209]
	v_lshl_add_u64 v[252:253], s[88:89], 0, v[212:213]
	s_add_u32 s2, s2, 0x80
	s_addc_u32 s3, s3, 0
	v_mfma_f32_16x16x32_bf16 v[102:105], v[150:153], v[166:169], v[102:105]
	v_mfma_f32_16x16x32_bf16 v[70:73], v[158:161], v[166:169], v[70:73]
	s_mov_b32 m0, s73
	s_nop 0
	global_load_lds_dwordx4 v[220:221], off
	v_mfma_f32_16x16x32_bf16 v[114:117], v[150:153], v[174:177], v[114:117]
	v_mfma_f32_16x16x32_bf16 v[82:85], v[158:161], v[174:177], v[82:85]
	s_mov_b32 m0, s75
	s_nop 0
	global_load_lds_dwordx4 v[222:223], off
	v_mfma_f32_16x16x32_bf16 v[110:113], v[150:153], v[182:185], v[110:113]
	v_mfma_f32_16x16x32_bf16 v[78:81], v[158:161], v[182:185], v[78:81]
	s_mov_b32 m0, s92
	s_nop 0
	global_load_lds_dwordx4 v[224:225], off
	v_mfma_f32_16x16x32_bf16 v[106:109], v[150:153], v[190:193], v[106:109]
	v_mfma_f32_16x16x32_bf16 v[74:77], v[158:161], v[190:193], v[74:77]
	s_mov_b32 m0, s93
	s_nop 0
	global_load_lds_dwordx4 v[252:253], off
	v_mfma_f32_16x16x32_bf16 v[102:105], v[154:157], v[170:173], v[102:105]
	v_mfma_f32_16x16x32_bf16 v[70:73], v[162:165], v[170:173], v[70:73]
	v_lshl_add_u64 v[220:221], s[84:85], 0, v[206:207]
	v_lshl_add_u64 v[222:223], s[84:85], 0, v[210:211]
	s_add_u32 s84, s84, 0x80
	s_addc_u32 s85, s85, 0
	v_mfma_f32_16x16x32_bf16 v[114:117], v[154:157], v[178:181], v[114:117]
	v_mfma_f32_16x16x32_bf16 v[82:85], v[162:165], v[178:181], v[82:85]
	s_mov_b32 m0, s61
	s_nop 0
	global_load_lds_dwordx4 v[220:221], off
	v_mfma_f32_16x16x32_bf16 v[110:113], v[154:157], v[186:189], v[110:113]
	v_mfma_f32_16x16x32_bf16 v[78:81], v[162:165], v[186:189], v[78:81]
	s_mov_b32 m0, s94
	s_nop 0
	global_load_lds_dwordx4 v[222:223], off
	v_mfma_f32_16x16x32_bf16 v[106:109], v[154:157], v[194:197], v[106:109]
	v_mfma_f32_16x16x32_bf16 v[74:77], v[162:165], v[194:197], v[74:77]
	v_mfma_f32_16x16x32_bf16 v[130:133], v[134:137], v[166:169], v[130:133]
	v_mfma_f32_16x16x32_bf16 v[98:101], v[142:145], v[166:169], v[98:101]
	v_mfma_f32_16x16x32_bf16 v[126:129], v[134:137], v[174:177], v[126:129]
	v_mfma_f32_16x16x32_bf16 v[94:97], v[142:145], v[174:177], v[94:97]
	v_mfma_f32_16x16x32_bf16 v[122:125], v[134:137], v[182:185], v[122:125]
	v_mfma_f32_16x16x32_bf16 v[90:93], v[142:145], v[182:185], v[90:93]
	v_mfma_f32_16x16x32_bf16 v[118:121], v[134:137], v[190:193], v[118:121]
	v_mfma_f32_16x16x32_bf16 v[86:89], v[142:145], v[190:193], v[86:89]
	v_mfma_f32_16x16x32_bf16 v[130:133], v[138:141], v[170:173], v[130:133]
	v_mfma_f32_16x16x32_bf16 v[98:101], v[146:149], v[170:173], v[98:101]
	v_mfma_f32_16x16x32_bf16 v[126:129], v[138:141], v[178:181], v[126:129]
	v_mfma_f32_16x16x32_bf16 v[94:97], v[146:149], v[178:181], v[94:97]
	v_mfma_f32_16x16x32_bf16 v[122:125], v[138:141], v[186:189], v[122:125]
	v_mfma_f32_16x16x32_bf16 v[90:93], v[146:149], v[186:189], v[90:93]
	v_mfma_f32_16x16x32_bf16 v[118:121], v[138:141], v[194:197], v[118:121]
	v_mfma_f32_16x16x32_bf16 v[86:89], v[146:149], v[194:197], v[86:89]
	s_waitcnt vmcnt(6)
	s_waitcnt lgkmcnt(0)
	s_barrier
	v_add_u32_e32 v3, 0xc000, v247
	v_add_u32_e32 v4, 0x20000, v247
	ds_read_b128 v[150:153], v3
	ds_read_b128 v[154:157], v3 offset:1024
	ds_read_b128 v[158:161], v3 offset:2048
	ds_read_b128 v[162:165], v3 offset:3072
	ds_read_b128 v[134:137], v4
	ds_read_b128 v[138:141], v4 offset:1024
	ds_read_b128 v[142:145], v4 offset:2048
	ds_read_b128 v[146:149], v4 offset:3072
	ds_read_b128 v[166:169], v250 offset:16384
	ds_read_b128 v[170:173], v250 offset:17408
	ds_read_b128 v[174:177], v250 offset:18432
	ds_read_b128 v[178:181], v250 offset:19456
	ds_read_b128 v[182:185], v250 offset:20480
	ds_read_b128 v[186:189], v250 offset:21504
	ds_read_b128 v[190:193], v250 offset:22528
	ds_read_b128 v[194:197], v250 offset:23552
	s_cmp_eq_u32 s45, 12
	s_cbranch_scc1 .Lhu_ns1
	v_lshl_add_u64 v[220:221], s[2:3], 0, v[208:209]
	v_lshl_add_u64 v[222:223], s[2:3], 0, v[212:213]
	s_add_u32 s88, s2, 0x40000
	s_addc_u32 s89, s3, 0
	v_lshl_add_u64 v[224:225], s[88:89], 0, v[208:209]
	v_lshl_add_u64 v[252:253], s[88:89], 0, v[212:213]
	s_add_u32 s2, s2, 0x80
	s_addc_u32 s3, s3, 0
	v_mfma_f32_16x16x32_bf16 v[102:105], v[22:25], v[38:41], v[102:105]
	v_mfma_f32_16x16x32_bf16 v[70:73], v[30:33], v[38:41], v[70:73]
	s_mov_b32 m0, s54
	s_nop 0
	global_load_lds_dwordx4 v[220:221], off
	v_mfma_f32_16x16x32_bf16 v[114:117], v[22:25], v[46:49], v[114:117]
	v_mfma_f32_16x16x32_bf16 v[82:85], v[30:33], v[46:49], v[82:85]
	s_mov_b32 m0, s55
	s_nop 0
	global_load_lds_dwordx4 v[222:223], off
	v_mfma_f32_16x16x32_bf16 v[110:113], v[22:25], v[54:57], v[110:113]
	v_mfma_f32_16x16x32_bf16 v[78:81], v[30:33], v[54:57], v[78:81]
	s_mov_b32 m0, s59
	s_nop 0
	global_load_lds_dwordx4 v[224:225], off
	v_mfma_f32_16x16x32_bf16 v[106:109], v[22:25], v[62:65], v[106:109]
	v_mfma_f32_16x16x32_bf16 v[74:77], v[30:33], v[62:65], v[74:77]
	s_mov_b32 m0, s24
	s_nop 0
	global_load_lds_dwordx4 v[252:253], off
	v_mfma_f32_16x16x32_bf16 v[102:105], v[26:29], v[42:45], v[102:105]
	v_mfma_f32_16x16x32_bf16 v[70:73], v[34:37], v[42:45], v[70:73]
	v_lshl_add_u64 v[220:221], s[84:85], 0, v[206:207]
	v_lshl_add_u64 v[222:223], s[84:85], 0, v[210:211]
	s_add_u32 s84, s84, 0x80
	s_addc_u32 s85, s85, 0
	v_mfma_f32_16x16x32_bf16 v[114:117], v[26:29], v[50:53], v[114:117]
	v_mfma_f32_16x16x32_bf16 v[82:85], v[34:37], v[50:53], v[82:85]
	s_mov_b32 m0, s57
	s_nop 0
	global_load_lds_dwordx4 v[220:221], off
	v_mfma_f32_16x16x32_bf16 v[110:113], v[26:29], v[58:61], v[110:113]
	v_mfma_f32_16x16x32_bf16 v[78:81], v[34:37], v[58:61], v[78:81]
	s_mov_b32 m0, s58
	s_nop 0
	global_load_lds_dwordx4 v[222:223], off
	v_mfma_f32_16x16x32_bf16 v[106:109], v[26:29], v[66:69], v[106:109]
	v_mfma_f32_16x16x32_bf16 v[74:77], v[34:37], v[66:69], v[74:77]
	v_mfma_f32_16x16x32_bf16 v[130:133], v[6:9], v[38:41], v[130:133]
	v_mfma_f32_16x16x32_bf16 v[98:101], v[14:17], v[38:41], v[98:101]
	v_mfma_f32_16x16x32_bf16 v[126:129], v[6:9], v[46:49], v[126:129]
	v_mfma_f32_16x16x32_bf16 v[94:97], v[14:17], v[46:49], v[94:97]
	v_mfma_f32_16x16x32_bf16 v[122:125], v[6:9], v[54:57], v[122:125]
	v_mfma_f32_16x16x32_bf16 v[90:93], v[14:17], v[54:57], v[90:93]
	v_mfma_f32_16x16x32_bf16 v[118:121], v[6:9], v[62:65], v[118:121]
	v_mfma_f32_16x16x32_bf16 v[86:89], v[14:17], v[62:65], v[86:89]
	v_mfma_f32_16x16x32_bf16 v[130:133], v[10:13], v[42:45], v[130:133]
	v_mfma_f32_16x16x32_bf16 v[98:101], v[18:21], v[42:45], v[98:101]
	v_mfma_f32_16x16x32_bf16 v[126:129], v[10:13], v[50:53], v[126:129]
	v_mfma_f32_16x16x32_bf16 v[94:97], v[18:21], v[50:53], v[94:97]
	v_mfma_f32_16x16x32_bf16 v[122:125], v[10:13], v[58:61], v[122:125]
	v_mfma_f32_16x16x32_bf16 v[90:93], v[18:21], v[58:61], v[90:93]
	v_mfma_f32_16x16x32_bf16 v[118:121], v[10:13], v[66:69], v[118:121]
	v_mfma_f32_16x16x32_bf16 v[86:89], v[18:21], v[66:69], v[86:89]
	s_branch .Lhu_nd1
.Lhu_ns1:
	v_mfma_f32_16x16x32_bf16 v[102:105], v[22:25], v[38:41], v[102:105]
	v_mfma_f32_16x16x32_bf16 v[70:73], v[30:33], v[38:41], v[70:73]
	v_mfma_f32_16x16x32_bf16 v[114:117], v[22:25], v[46:49], v[114:117]
	v_mfma_f32_16x16x32_bf16 v[82:85], v[30:33], v[46:49], v[82:85]
	v_mfma_f32_16x16x32_bf16 v[110:113], v[22:25], v[54:57], v[110:113]
	v_mfma_f32_16x16x32_bf16 v[78:81], v[30:33], v[54:57], v[78:81]
	v_mfma_f32_16x16x32_bf16 v[106:109], v[22:25], v[62:65], v[106:109]
	v_mfma_f32_16x16x32_bf16 v[74:77], v[30:33], v[62:65], v[74:77]
	v_mfma_f32_16x16x32_bf16 v[102:105], v[26:29], v[42:45], v[102:105]
	v_mfma_f32_16x16x32_bf16 v[70:73], v[34:37], v[42:45], v[70:73]
	v_mfma_f32_16x16x32_bf16 v[114:117], v[26:29], v[50:53], v[114:117]
	v_mfma_f32_16x16x32_bf16 v[82:85], v[34:37], v[50:53], v[82:85]
	v_mfma_f32_16x16x32_bf16 v[110:113], v[26:29], v[58:61], v[110:113]
	v_mfma_f32_16x16x32_bf16 v[78:81], v[34:37], v[58:61], v[78:81]
	v_mfma_f32_16x16x32_bf16 v[106:109], v[26:29], v[66:69], v[106:109]
	v_mfma_f32_16x16x32_bf16 v[74:77], v[34:37], v[66:69], v[74:77]
	v_mfma_f32_16x16x32_bf16 v[130:133], v[6:9], v[38:41], v[130:133]
	v_mfma_f32_16x16x32_bf16 v[98:101], v[14:17], v[38:41], v[98:101]
	v_mfma_f32_16x16x32_bf16 v[126:129], v[6:9], v[46:49], v[126:129]
	v_mfma_f32_16x16x32_bf16 v[94:97], v[14:17], v[46:49], v[94:97]
	v_mfma_f32_16x16x32_bf16 v[122:125], v[6:9], v[54:57], v[122:125]
	v_mfma_f32_16x16x32_bf16 v[90:93], v[14:17], v[54:57], v[90:93]
	v_mfma_f32_16x16x32_bf16 v[118:121], v[6:9], v[62:65], v[118:121]
	v_mfma_f32_16x16x32_bf16 v[86:89], v[14:17], v[62:65], v[86:89]
	v_mfma_f32_16x16x32_bf16 v[130:133], v[10:13], v[42:45], v[130:133]
	v_mfma_f32_16x16x32_bf16 v[98:101], v[18:21], v[42:45], v[98:101]
	v_mfma_f32_16x16x32_bf16 v[126:129], v[10:13], v[50:53], v[126:129]
	v_mfma_f32_16x16x32_bf16 v[94:97], v[18:21], v[50:53], v[94:97]
	v_mfma_f32_16x16x32_bf16 v[122:125], v[10:13], v[58:61], v[122:125]
	v_mfma_f32_16x16x32_bf16 v[90:93], v[18:21], v[58:61], v[90:93]
	v_mfma_f32_16x16x32_bf16 v[118:121], v[10:13], v[66:69], v[118:121]
	v_mfma_f32_16x16x32_bf16 v[86:89], v[18:21], v[66:69], v[86:89]

.Lhu_w2b:
	s_waitcnt lgkmcnt(0)
	s_barrier
	ds_read_b128 v[22:25], v248
	ds_read_b128 v[26:29], v248 offset:1024
	ds_read_b128 v[30:33], v248 offset:2048
	ds_read_b128 v[34:37], v248 offset:3072
	ds_read_b128 v[6:9], v249
	ds_read_b128 v[10:13], v249 offset:1024
	ds_read_b128 v[14:17], v249 offset:2048
	ds_read_b128 v[18:21], v249 offset:3072
	ds_read_b128 v[38:41], v250
	ds_read_b128 v[42:45], v250 offset:1024
	ds_read_b128 v[46:49], v250 offset:2048
	ds_read_b128 v[50:53], v250 offset:3072
	ds_read_b128 v[54:57], v250 offset:4096
	ds_read_b128 v[58:61], v250 offset:5120
	ds_read_b128 v[62:65], v250 offset:6144
	ds_read_b128 v[66:69], v250 offset:7168
	s_cmp_eq_u32 s45, 12
	s_cbranch_scc1 .Lhu_ns2
	v_lshl_add_u64 v[220:221], s[2:3], 0, v[208:209]
	v_lshl_add_u64 v[222:223], s[2:3], 0, v[212:213]
	s_add_u32 s88, s2, 0x40000
	s_addc_u32 s89, s3, 0
	v_lshl_add_u64 v[224:225], s[88:89], 0, v[208:209]
	v_lshl_add_u64 v[252:253], s[88:89], 0, v[212:213]
	s_add_u32 s2, s2, 0x80
	s_addc_u32 s3, s3, 0
	v_mfma_f32_16x16x32_bf16 v[102:105], v[150:153], v[166:169], v[102:105]
	v_mfma_f32_16x16x32_bf16 v[70:73], v[158:161], v[166:169], v[70:73]
	s_add_i32 m0, s61, 0xc000
	s_nop 0
	global_load_lds_dwordx4 v[220:221], off
	v_mfma_f32_16x16x32_bf16 v[114:117], v[150:153], v[174:177], v[114:117]
	v_mfma_f32_16x16x32_bf16 v[82:85], v[158:161], v[174:177], v[82:85]
	s_add_i32 m0, s61, 0xe000
	s_nop 0
	global_load_lds_dwordx4 v[222:223], off
	v_mfma_f32_16x16x32_bf16 v[110:113], v[150:153], v[182:185], v[110:113]
	v_mfma_f32_16x16x32_bf16 v[78:81], v[158:161], v[182:185], v[78:81]
	s_add_i32 m0, s61, 0x20000
	s_nop 0
	global_load_lds_dwordx4 v[224:225], off
	v_mfma_f32_16x16x32_bf16 v[106:109], v[150:153], v[190:193], v[106:109]
	v_mfma_f32_16x16x32_bf16 v[74:77], v[158:161], v[190:193], v[74:77]
	s_add_i32 m0, s61, 0x22000
	s_nop 0
	global_load_lds_dwordx4 v[252:253], off
	v_mfma_f32_16x16x32_bf16 v[102:105], v[154:157], v[170:173], v[102:105]
	v_mfma_f32_16x16x32_bf16 v[70:73], v[162:165], v[170:173], v[70:73]
	v_lshl_add_u64 v[220:221], s[84:85], 0, v[206:207]
	v_lshl_add_u64 v[222:223], s[84:85], 0, v[210:211]
	s_add_u32 s84, s84, 0x80
	s_addc_u32 s85, s85, 0
	v_mfma_f32_16x16x32_bf16 v[114:117], v[154:157], v[178:181], v[114:117]
	v_mfma_f32_16x16x32_bf16 v[82:85], v[162:165], v[178:181], v[82:85]
	s_mov_b32 m0, s95
	s_nop 0
	global_load_lds_dwordx4 v[220:221], off
	v_mfma_f32_16x16x32_bf16 v[110:113], v[154:157], v[186:189], v[110:113]
	v_mfma_f32_16x16x32_bf16 v[78:81], v[162:165], v[186:189], v[78:81]
	s_mov_b32 m0, s96
	s_nop 0
	global_load_lds_dwordx4 v[222:223], off
	v_mfma_f32_16x16x32_bf16 v[106:109], v[154:157], v[194:197], v[106:109]
	v_mfma_f32_16x16x32_bf16 v[74:77], v[162:165], v[194:197], v[74:77]
	v_mfma_f32_16x16x32_bf16 v[130:133], v[134:137], v[166:169], v[130:133]
	v_mfma_f32_16x16x32_bf16 v[98:101], v[142:145], v[166:169], v[98:101]
	v_mfma_f32_16x16x32_bf16 v[126:129], v[134:137], v[174:177], v[126:129]
	v_mfma_f32_16x16x32_bf16 v[94:97], v[142:145], v[174:177], v[94:97]
	v_mfma_f32_16x16x32_bf16 v[122:125], v[134:137], v[182:185], v[122:125]
	v_mfma_f32_16x16x32_bf16 v[90:93], v[142:145], v[182:185], v[90:93]
	v_mfma_f32_16x16x32_bf16 v[118:121], v[134:137], v[190:193], v[118:121]
	v_mfma_f32_16x16x32_bf16 v[86:89], v[142:145], v[190:193], v[86:89]
	v_mfma_f32_16x16x32_bf16 v[130:133], v[138:141], v[170:173], v[130:133]
	v_mfma_f32_16x16x32_bf16 v[98:101], v[146:149], v[170:173], v[98:101]
	v_mfma_f32_16x16x32_bf16 v[126:129], v[138:141], v[178:181], v[126:129]
	v_mfma_f32_16x16x32_bf16 v[94:97], v[146:149], v[178:181], v[94:97]
	v_mfma_f32_16x16x32_bf16 v[122:125], v[138:141], v[186:189], v[122:125]
	v_mfma_f32_16x16x32_bf16 v[90:93], v[146:149], v[186:189], v[90:93]
	v_mfma_f32_16x16x32_bf16 v[118:121], v[138:141], v[194:197], v[118:121]
	v_mfma_f32_16x16x32_bf16 v[86:89], v[146:149], v[194:197], v[86:89]
	s_branch .Lhu_nd2
.Lhu_ns2:
	v_mfma_f32_16x16x32_bf16 v[102:105], v[150:153], v[166:169], v[102:105]
	v_mfma_f32_16x16x32_bf16 v[70:73], v[158:161], v[166:169], v[70:73]
	v_mfma_f32_16x16x32_bf16 v[114:117], v[150:153], v[174:177], v[114:117]
	v_mfma_f32_16x16x32_bf16 v[82:85], v[158:161], v[174:177], v[82:85]
	v_mfma_f32_16x16x32_bf16 v[110:113], v[150:153], v[182:185], v[110:113]
	v_mfma_f32_16x16x32_bf16 v[78:81], v[158:161], v[182:185], v[78:81]
	v_mfma_f32_16x16x32_bf16 v[106:109], v[150:153], v[190:193], v[106:109]
	v_mfma_f32_16x16x32_bf16 v[74:77], v[158:161], v[190:193], v[74:77]
	v_mfma_f32_16x16x32_bf16 v[102:105], v[154:157], v[170:173], v[102:105]
	v_mfma_f32_16x16x32_bf16 v[70:73], v[162:165], v[170:173], v[70:73]
	v_mfma_f32_16x16x32_bf16 v[114:117], v[154:157], v[178:181], v[114:117]
	v_mfma_f32_16x16x32_bf16 v[82:85], v[162:165], v[178:181], v[82:85]
	v_mfma_f32_16x16x32_bf16 v[110:113], v[154:157], v[186:189], v[110:113]
	v_mfma_f32_16x16x32_bf16 v[78:81], v[162:165], v[186:189], v[78:81]
	v_mfma_f32_16x16x32_bf16 v[106:109], v[154:157], v[194:197], v[106:109]
	v_mfma_f32_16x16x32_bf16 v[74:77], v[162:165], v[194:197], v[74:77]
	v_mfma_f32_16x16x32_bf16 v[130:133], v[134:137], v[166:169], v[130:133]
	v_mfma_f32_16x16x32_bf16 v[98:101], v[142:145], v[166:169], v[98:101]
	v_mfma_f32_16x16x32_bf16 v[126:129], v[134:137], v[174:177], v[126:129]
	v_mfma_f32_16x16x32_bf16 v[94:97], v[142:145], v[174:177], v[94:97]
	v_mfma_f32_16x16x32_bf16 v[122:125], v[134:137], v[182:185], v[122:125]
	v_mfma_f32_16x16x32_bf16 v[90:93], v[142:145], v[182:185], v[90:93]
	v_mfma_f32_16x16x32_bf16 v[118:121], v[134:137], v[190:193], v[118:121]
	v_mfma_f32_16x16x32_bf16 v[86:89], v[142:145], v[190:193], v[86:89]
	v_mfma_f32_16x16x32_bf16 v[130:133], v[138:141], v[170:173], v[130:133]
	v_mfma_f32_16x16x32_bf16 v[98:101], v[146:149], v[170:173], v[98:101]
	v_mfma_f32_16x16x32_bf16 v[126:129], v[138:141], v[178:181], v[126:129]
	v_mfma_f32_16x16x32_bf16 v[94:97], v[146:149], v[178:181], v[94:97]
	v_mfma_f32_16x16x32_bf16 v[122:125], v[138:141], v[186:189], v[122:125]
	v_mfma_f32_16x16x32_bf16 v[90:93], v[146:149], v[186:189], v[90:93]
	v_mfma_f32_16x16x32_bf16 v[118:121], v[138:141], v[194:197], v[118:121]
	v_mfma_f32_16x16x32_bf16 v[86:89], v[146:149], v[194:197], v[86:89]
.Lhu_nd2:
	s_cmp_eq_u32 s45, 12
	s_cbranch_scc1 .Lhu_tail
	s_waitcnt vmcnt(6)
	s_waitcnt lgkmcnt(0)
	s_barrier
	v_add_u32_e32 v3, 0x18000, v247
	v_add_u32_e32 v4, 0x1c000, v247
	ds_read_b128 v[150:153], v3
	ds_read_b128 v[154:157], v3 offset:1024
	ds_read_b128 v[158:161], v3 offset:2048
	ds_read_b128 v[162:165], v3 offset:3072
	ds_read_b128 v[134:137], v4
	ds_read_b128 v[138:141], v4 offset:1024
	ds_read_b128 v[142:145], v4 offset:2048
	ds_read_b128 v[146:149], v4 offset:3072
	ds_read_b128 v[166:169], v250 offset:32768
	ds_read_b128 v[170:173], v250 offset:33792
	ds_read_b128 v[174:177], v250 offset:34816
	ds_read_b128 v[178:181], v250 offset:35840
	ds_read_b128 v[182:185], v250 offset:36864
	ds_read_b128 v[186:189], v250 offset:37888
	ds_read_b128 v[190:193], v250 offset:38912
	ds_read_b128 v[194:197], v250 offset:39936
	v_lshl_add_u64 v[220:221], s[2:3], 0, v[208:209]
	v_lshl_add_u64 v[222:223], s[2:3], 0, v[212:213]
	s_add_u32 s88, s2, 0x40000
	s_addc_u32 s89, s3, 0
	v_lshl_add_u64 v[224:225], s[88:89], 0, v[208:209]
	v_lshl_add_u64 v[252:253], s[88:89], 0, v[212:213]
	s_add_u32 s2, s2, 0x80
	s_addc_u32 s3, s3, 0
	v_mfma_f32_16x16x32_bf16 v[102:105], v[22:25], v[38:41], v[102:105]
	v_mfma_f32_16x16x32_bf16 v[70:73], v[30:33], v[38:41], v[70:73]
	s_mov_b32 m0, s73
	s_nop 0
	global_load_lds_dwordx4 v[220:221], off
	v_mfma_f32_16x16x32_bf16 v[114:117], v[22:25], v[46:49], v[114:117]
	v_mfma_f32_16x16x32_bf16 v[82:85], v[30:33], v[46:49], v[82:85]
	s_mov_b32 m0, s75
	s_nop 0
	global_load_lds_dwordx4 v[222:223], off
	v_mfma_f32_16x16x32_bf16 v[110:113], v[22:25], v[54:57], v[110:113]
	v_mfma_f32_16x16x32_bf16 v[78:81], v[30:33], v[54:57], v[78:81]
	s_mov_b32 m0, s92
	s_nop 0
	global_load_lds_dwordx4 v[224:225], off
	v_mfma_f32_16x16x32_bf16 v[106:109], v[22:25], v[62:65], v[106:109]
	v_mfma_f32_16x16x32_bf16 v[74:77], v[30:33], v[62:65], v[74:77]
	s_mov_b32 m0, s93
	s_nop 0
	global_load_lds_dwordx4 v[252:253], off
	v_mfma_f32_16x16x32_bf16 v[102:105], v[26:29], v[42:45], v[102:105]
	v_mfma_f32_16x16x32_bf16 v[70:73], v[34:37], v[42:45], v[70:73]
	v_lshl_add_u64 v[220:221], s[84:85], 0, v[206:207]
	v_lshl_add_u64 v[222:223], s[84:85], 0, v[210:211]
	s_add_u32 s84, s84, 0x80
	s_addc_u32 s85, s85, 0
	v_mfma_f32_16x16x32_bf16 v[114:117], v[26:29], v[50:53], v[114:117]
	v_mfma_f32_16x16x32_bf16 v[82:85], v[34:37], v[50:53], v[82:85]
	s_mov_b32 m0, s61
	s_nop 0
	global_load_lds_dwordx4 v[220:221], off
	v_mfma_f32_16x16x32_bf16 v[110:113], v[26:29], v[58:61], v[110:113]
	v_mfma_f32_16x16x32_bf16 v[78:81], v[34:37], v[58:61], v[78:81]
	s_mov_b32 m0, s94
	s_nop 0
	global_load_lds_dwordx4 v[222:223], off
	v_mfma_f32_16x16x32_bf16 v[106:109], v[26:29], v[66:69], v[106:109]
	v_mfma_f32_16x16x32_bf16 v[74:77], v[34:37], v[66:69], v[74:77]
	v_mfma_f32_16x16x32_bf16 v[130:133], v[6:9], v[38:41], v[130:133]
	v_mfma_f32_16x16x32_bf16 v[98:101], v[14:17], v[38:41], v[98:101]
	v_mfma_f32_16x16x32_bf16 v[126:129], v[6:9], v[46:49], v[126:129]
	v_mfma_f32_16x16x32_bf16 v[94:97], v[14:17], v[46:49], v[94:97]
	v_mfma_f32_16x16x32_bf16 v[122:125], v[6:9], v[54:57], v[122:125]
	v_mfma_f32_16x16x32_bf16 v[90:93], v[14:17], v[54:57], v[90:93]
	v_mfma_f32_16x16x32_bf16 v[118:121], v[6:9], v[62:65], v[118:121]
	v_mfma_f32_16x16x32_bf16 v[86:89], v[14:17], v[62:65], v[86:89]
	v_mfma_f32_16x16x32_bf16 v[130:133], v[10:13], v[42:45], v[130:133]
	v_mfma_f32_16x16x32_bf16 v[98:101], v[18:21], v[42:45], v[98:101]
	v_mfma_f32_16x16x32_bf16 v[126:129], v[10:13], v[50:53], v[126:129]
	v_mfma_f32_16x16x32_bf16 v[94:97], v[18:21], v[50:53], v[94:97]
	v_mfma_f32_16x16x32_bf16 v[122:125], v[10:13], v[58:61], v[122:125]
	v_mfma_f32_16x16x32_bf16 v[90:93], v[18:21], v[58:61], v[90:93]
	v_mfma_f32_16x16x32_bf16 v[118:121], v[10:13], v[66:69], v[118:121]
	v_mfma_f32_16x16x32_bf16 v[86:89], v[18:21], v[66:69], v[86:89]
	s_waitcnt vmcnt(6)
	s_waitcnt lgkmcnt(0)
	s_barrier
	v_add_u32_e32 v3, 0xc000, v247
	v_add_u32_e32 v4, 0x20000, v247
	ds_read_b128 v[22:25], v3
	ds_read_b128 v[26:29], v3 offset:1024
	ds_read_b128 v[30:33], v3 offset:2048
	ds_read_b128 v[34:37], v3 offset:3072
	ds_read_b128 v[6:9], v4
	ds_read_b128 v[10:13], v4 offset:1024
	ds_read_b128 v[14:17], v4 offset:2048
	ds_read_b128 v[18:21], v4 offset:3072
	ds_read_b128 v[38:41], v250 offset:16384
	ds_read_b128 v[42:45], v250 offset:17408
	ds_read_b128 v[46:49], v250 offset:18432
	ds_read_b128 v[50:53], v250 offset:19456
	ds_read_b128 v[54:57], v250 offset:20480
	ds_read_b128 v[58:61], v250 offset:21504
	ds_read_b128 v[62:65], v250 offset:22528
	ds_read_b128 v[66:69], v250 offset:23552
	v_lshl_add_u64 v[220:221], s[2:3], 0, v[208:209]
	v_lshl_add_u64 v[222:223], s[2:3], 0, v[212:213]
	s_add_u32 s88, s2, 0x40000
	s_addc_u32 s89, s3, 0
	v_lshl_add_u64 v[224:225], s[88:89], 0, v[208:209]
	v_lshl_add_u64 v[252:253], s[88:89], 0, v[212:213]
	s_add_u32 s2, s2, 0x80
	s_addc_u32 s3, s3, 0
	v_mfma_f32_16x16x32_bf16 v[102:105], v[150:153], v[166:169], v[102:105]
	v_mfma_f32_16x16x32_bf16 v[70:73], v[158:161], v[166:169], v[70:73]
	s_mov_b32 m0, s54
	s_nop 0
	global_load_lds_dwordx4 v[220:221], off
	v_mfma_f32_16x16x32_bf16 v[114:117], v[150:153], v[174:177], v[114:117]
	v_mfma_f32_16x16x32_bf16 v[82:85], v[158:161], v[174:177], v[82:85]
	s_mov_b32 m0, s55
	s_nop 0
	global_load_lds_dwordx4 v[222:223], off
	v_mfma_f32_16x16x32_bf16 v[110:113], v[150:153], v[182:185], v[110:113]
	v_mfma_f32_16x16x32_bf16 v[78:81], v[158:161], v[182:185], v[78:81]
	s_mov_b32 m0, s59
	s_nop 0
	global_load_lds_dwordx4 v[224:225], off
	v_mfma_f32_16x16x32_bf16 v[106:109], v[150:153], v[190:193], v[106:109]
	v_mfma_f32_16x16x32_bf16 v[74:77], v[158:161], v[190:193], v[74:77]
	s_mov_b32 m0, s24
	s_nop 0
	global_load_lds_dwordx4 v[252:253], off
	v_mfma_f32_16x16x32_bf16 v[102:105], v[154:157], v[170:173], v[102:105]
	v_mfma_f32_16x16x32_bf16 v[70:73], v[162:165], v[170:173], v[70:73]
	v_lshl_add_u64 v[220:221], s[84:85], 0, v[206:207]
	v_lshl_add_u64 v[222:223], s[84:85], 0, v[210:211]
	s_add_u32 s84, s84, 0x80
	s_addc_u32 s85, s85, 0
	v_mfma_f32_16x16x32_bf16 v[114:117], v[154:157], v[178:181], v[114:117]
	v_mfma_f32_16x16x32_bf16 v[82:85], v[162:165], v[178:181], v[82:85]
	s_mov_b32 m0, s57
	s_nop 0
	global_load_lds_dwordx4 v[220:221], off
	v_mfma_f32_16x16x32_bf16 v[110:113], v[154:157], v[186:189], v[110:113]
	v_mfma_f32_16x16x32_bf16 v[78:81], v[162:165], v[186:189], v[78:81]
	s_mov_b32 m0, s58
	s_nop 0
	global_load_lds_dwordx4 v[222:223], off
	v_mfma_f32_16x16x32_bf16 v[106:109], v[154:157], v[194:197], v[106:109]
	v_mfma_f32_16x16x32_bf16 v[74:77], v[162:165], v[194:197], v[74:77]
	v_mfma_f32_16x16x32_bf16 v[130:133], v[134:137], v[166:169], v[130:133]
	v_mfma_f32_16x16x32_bf16 v[98:101], v[142:145], v[166:169], v[98:101]
	v_mfma_f32_16x16x32_bf16 v[126:129], v[134:137], v[174:177], v[126:129]
	v_mfma_f32_16x16x32_bf16 v[94:97], v[142:145], v[174:177], v[94:97]
	v_mfma_f32_16x16x32_bf16 v[122:125], v[134:137], v[182:185], v[122:125]
	v_mfma_f32_16x16x32_bf16 v[90:93], v[142:145], v[182:185], v[90:93]
	v_mfma_f32_16x16x32_bf16 v[118:121], v[134:137], v[190:193], v[118:121]
	v_mfma_f32_16x16x32_bf16 v[86:89], v[142:145], v[190:193], v[86:89]
	v_mfma_f32_16x16x32_bf16 v[130:133], v[138:141], v[170:173], v[130:133]
	v_mfma_f32_16x16x32_bf16 v[98:101], v[146:149], v[170:173], v[98:101]
	v_mfma_f32_16x16x32_bf16 v[126:129], v[138:141], v[178:181], v[126:129]
	v_mfma_f32_16x16x32_bf16 v[94:97], v[146:149], v[178:181], v[94:97]
	v_mfma_f32_16x16x32_bf16 v[122:125], v[138:141], v[186:189], v[122:125]
	v_mfma_f32_16x16x32_bf16 v[90:93], v[146:149], v[186:189], v[90:93]
	v_mfma_f32_16x16x32_bf16 v[118:121], v[138:141], v[194:197], v[118:121]
	v_mfma_f32_16x16x32_bf16 v[86:89], v[146:149], v[194:197], v[86:89]
	s_waitcnt vmcnt(6)
	s_waitcnt lgkmcnt(0)
	s_barrier
	ds_read_b128 v[150:153], v248
	ds_read_b128 v[154:157], v248 offset:1024
	ds_read_b128 v[158:161], v248 offset:2048
	ds_read_b128 v[162:165], v248 offset:3072
	ds_read_b128 v[134:137], v249
	ds_read_b128 v[138:141], v249 offset:1024
	ds_read_b128 v[142:145], v249 offset:2048
	ds_read_b128 v[146:149], v249 offset:3072
	ds_read_b128 v[166:169], v250
	ds_read_b128 v[170:173], v250 offset:1024
	ds_read_b128 v[174:177], v250 offset:2048
	ds_read_b128 v[178:181], v250 offset:3072
	ds_read_b128 v[182:185], v250 offset:4096
	ds_read_b128 v[186:189], v250 offset:5120
	ds_read_b128 v[190:193], v250 offset:6144
	ds_read_b128 v[194:197], v250 offset:7168
	v_lshl_add_u64 v[220:221], s[2:3], 0, v[208:209]
	v_lshl_add_u64 v[222:223], s[2:3], 0, v[212:213]
	s_add_u32 s88, s2, 0x40000
	s_addc_u32 s89, s3, 0
	v_lshl_add_u64 v[224:225], s[88:89], 0, v[208:209]
	v_lshl_add_u64 v[252:253], s[88:89], 0, v[212:213]
	s_add_u32 s2, s2, 0x80
	s_addc_u32 s3, s3, 0
	v_mfma_f32_16x16x32_bf16 v[102:105], v[22:25], v[38:41], v[102:105]
	v_mfma_f32_16x16x32_bf16 v[70:73], v[30:33], v[38:41], v[70:73]
	s_add_i32 m0, s61, 0xc000
	s_nop 0
	global_load_lds_dwordx4 v[220:221], off
	v_mfma_f32_16x16x32_bf16 v[114:117], v[22:25], v[46:49], v[114:117]
	v_mfma_f32_16x16x32_bf16 v[82:85], v[30:33], v[46:49], v[82:85]
	s_add_i32 m0, s61, 0xe000
	s_nop 0
	global_load_lds_dwordx4 v[222:223], off
	v_mfma_f32_16x16x32_bf16 v[110:113], v[22:25], v[54:57], v[110:113]
	v_mfma_f32_16x16x32_bf16 v[78:81], v[30:33], v[54:57], v[78:81]
	s_add_i32 m0, s61, 0x20000
	s_nop 0
	global_load_lds_dwordx4 v[224:225], off
	v_mfma_f32_16x16x32_bf16 v[106:109], v[22:25], v[62:65], v[106:109]
	v_mfma_f32_16x16x32_bf16 v[74:77], v[30:33], v[62:65], v[74:77]
	s_add_i32 m0, s61, 0x22000
	s_nop 0
	global_load_lds_dwordx4 v[252:253], off
	v_mfma_f32_16x16x32_bf16 v[102:105], v[26:29], v[42:45], v[102:105]
	v_mfma_f32_16x16x32_bf16 v[70:73], v[34:37], v[42:45], v[70:73]
	v_lshl_add_u64 v[220:221], s[84:85], 0, v[206:207]
	v_lshl_add_u64 v[222:223], s[84:85], 0, v[210:211]
	s_add_u32 s84, s84, 0x80
	s_addc_u32 s85, s85, 0
	v_mfma_f32_16x16x32_bf16 v[114:117], v[26:29], v[50:53], v[114:117]
	v_mfma_f32_16x16x32_bf16 v[82:85], v[34:37], v[50:53], v[82:85]
	s_mov_b32 m0, s95
	s_nop 0
	global_load_lds_dwordx4 v[220:221], off
	v_mfma_f32_16x16x32_bf16 v[110:113], v[26:29], v[58:61], v[110:113]
	v_mfma_f32_16x16x32_bf16 v[78:81], v[34:37], v[58:61], v[78:81]
	s_mov_b32 m0, s96
	s_nop 0
	global_load_lds_dwordx4 v[222:223], off
	v_mfma_f32_16x16x32_bf16 v[106:109], v[26:29], v[66:69], v[106:109]
	v_mfma_f32_16x16x32_bf16 v[74:77], v[34:37], v[66:69], v[74:77]
	v_mfma_f32_16x16x32_bf16 v[130:133], v[6:9], v[38:41], v[130:133]
	v_mfma_f32_16x16x32_bf16 v[98:101], v[14:17], v[38:41], v[98:101]
	v_mfma_f32_16x16x32_bf16 v[126:129], v[6:9], v[46:49], v[126:129]
	v_mfma_f32_16x16x32_bf16 v[94:97], v[14:17], v[46:49], v[94:97]
	v_mfma_f32_16x16x32_bf16 v[122:125], v[6:9], v[54:57], v[122:125]
	v_mfma_f32_16x16x32_bf16 v[90:93], v[14:17], v[54:57], v[90:93]
	v_mfma_f32_16x16x32_bf16 v[118:121], v[6:9], v[62:65], v[118:121]
	v_mfma_f32_16x16x32_bf16 v[86:89], v[14:17], v[62:65], v[86:89]
	v_mfma_f32_16x16x32_bf16 v[130:133], v[10:13], v[42:45], v[130:133]
	v_mfma_f32_16x16x32_bf16 v[98:101], v[18:21], v[42:45], v[98:101]
	v_mfma_f32_16x16x32_bf16 v[126:129], v[10:13], v[50:53], v[126:129]
	v_mfma_f32_16x16x32_bf16 v[94:97], v[18:21], v[50:53], v[94:97]
	v_mfma_f32_16x16x32_bf16 v[122:125], v[10:13], v[58:61], v[122:125]
	v_mfma_f32_16x16x32_bf16 v[90:93], v[18:21], v[58:61], v[90:93]
	v_mfma_f32_16x16x32_bf16 v[118:121], v[10:13], v[66:69], v[118:121]
	v_mfma_f32_16x16x32_bf16 v[86:89], v[18:21], v[66:69], v[86:89]
	s_add_i32 s45, s45, 6
	s_branch .Lhu_loop
.Lhu_tail:
	s_waitcnt lgkmcnt(0)
	v_mfma_f32_16x16x32_bf16 v[102:105], v[22:25], v[38:41], v[102:105]
	v_mfma_f32_16x16x32_bf16 v[70:73], v[30:33], v[38:41], v[70:73]
	v_mfma_f32_16x16x32_bf16 v[114:117], v[22:25], v[46:49], v[114:117]
	v_mfma_f32_16x16x32_bf16 v[82:85], v[30:33], v[46:49], v[82:85]
	v_mfma_f32_16x16x32_bf16 v[110:113], v[22:25], v[54:57], v[110:113]
	v_mfma_f32_16x16x32_bf16 v[78:81], v[30:33], v[54:57], v[78:81]
	v_mfma_f32_16x16x32_bf16 v[106:109], v[22:25], v[62:65], v[106:109]
	v_mfma_f32_16x16x32_bf16 v[74:77], v[30:33], v[62:65], v[74:77]
	v_mfma_f32_16x16x32_bf16 v[102:105], v[26:29], v[42:45], v[102:105]
	v_mfma_f32_16x16x32_bf16 v[70:73], v[34:37], v[42:45], v[70:73]
	v_mfma_f32_16x16x32_bf16 v[114:117], v[26:29], v[50:53], v[114:117]
	v_mfma_f32_16x16x32_bf16 v[82:85], v[34:37], v[50:53], v[82:85]
	v_mfma_f32_16x16x32_bf16 v[110:113], v[26:29], v[58:61], v[110:113]
	v_mfma_f32_16x16x32_bf16 v[78:81], v[34:37], v[58:61], v[78:81]
	v_mfma_f32_16x16x32_bf16 v[106:109], v[26:29], v[66:69], v[106:109]
	v_mfma_f32_16x16x32_bf16 v[74:77], v[34:37], v[66:69], v[74:77]
	v_mfma_f32_16x16x32_bf16 v[130:133], v[6:9], v[38:41], v[130:133]
	v_mfma_f32_16x16x32_bf16 v[98:101], v[14:17], v[38:41], v[98:101]
	v_mfma_f32_16x16x32_bf16 v[126:129], v[6:9], v[46:49], v[126:129]
	v_mfma_f32_16x16x32_bf16 v[94:97], v[14:17], v[46:49], v[94:97]
	v_mfma_f32_16x16x32_bf16 v[122:125], v[6:9], v[54:57], v[122:125]
	v_mfma_f32_16x16x32_bf16 v[90:93], v[14:17], v[54:57], v[90:93]
	v_mfma_f32_16x16x32_bf16 v[118:121], v[6:9], v[62:65], v[118:121]
	v_mfma_f32_16x16x32_bf16 v[86:89], v[14:17], v[62:65], v[86:89]
	v_mfma_f32_16x16x32_bf16 v[130:133], v[10:13], v[42:45], v[130:133]
	v_mfma_f32_16x16x32_bf16 v[98:101], v[18:21], v[42:45], v[98:101]
	v_mfma_f32_16x16x32_bf16 v[126:129], v[10:13], v[50:53], v[126:129]
	v_mfma_f32_16x16x32_bf16 v[94:97], v[18:21], v[50:53], v[94:97]
	v_mfma_f32_16x16x32_bf16 v[122:125], v[10:13], v[58:61], v[122:125]
	v_mfma_f32_16x16x32_bf16 v[90:93], v[18:21], v[58:61], v[90:93]
	v_mfma_f32_16x16x32_bf16 v[118:121], v[10:13], v[66:69], v[118:121]
	v_mfma_f32_16x16x32_bf16 v[86:89], v[18:21], v[66:69], v[86:89]
	s_and_b64 vcc, exec, s[14:15]
	s_cbranch_vccnz .Lhu_out
	s_barrier
.Lhu_out:
	s_mov_b64 s[0:1], -1
	s_branch .LBB0_122
